# grid barrier: early invalidate issued right after the arrival atomic, counted wait so the last arriver does not wait for it before its write-back
# speedup vs baseline: 1.0208x; 1.0041x over previous
.LBB0_63:
	s_or_b64 exec, exec, s[4:5]
	buffer_inv sc1
	v_cvt_f32_u32_e32 v4, v2
	s_waitcnt vmcnt(1)
	v_readfirstlane_b32 s0, v3
	v_sub_u32_e32 v3, 0, v2
	v_rcp_iflag_f32_e32 v4, v4
	v_add_u32_e32 v5, s0, v1
	v_mul_f32_e32 v4, 0x4f7ffffe, v4
	v_cvt_u32_f32_e32 v4, v4
	v_mul_lo_u32 v1, v3, v4
	v_mul_hi_u32 v1, v4, v1
	v_add_u32_e32 v1, v4, v1
	v_mul_hi_u32 v1, v5, v1
	v_mul_lo_u32 v3, v1, v2
	v_sub_u32_e32 v3, v5, v3
	v_add_u32_e32 v4, 1, v1
	v_cmp_ge_u32_e32 vcc, v3, v2
	s_nop 1
	v_cndmask_b32_e32 v1, v1, v4, vcc
	v_sub_u32_e32 v4, v3, v2
	v_cndmask_b32_e32 v3, v3, v4, vcc
	v_add_u32_e32 v4, 1, v1
	v_cmp_ge_u32_e32 vcc, v3, v2
	v_add_u32_e32 v3, 1, v5
	s_nop 0
	v_cndmask_b32_e32 v1, v1, v4, vcc
	v_mul_lo_u32 v4, v2, v1
	v_add_u32_e32 v2, v4, v2
	v_cmp_ne_u32_e32 vcc, v3, v2
	s_and_saveexec_b64 s[0:1], vcc
	s_xor_b64 s[4:5], exec, s[0:1]
	s_cbranch_execz .LBB0_77
	s_waitcnt lgkmcnt(0)
	v_mov_b32_e32 v0, 0x2000
	global_load_dword v0, v0, s[8:9] offset:1024 sc1
	s_add_u32 s12, s8, 0x2400
	s_addc_u32 s13, s9, 0
	s_waitcnt vmcnt(0)
	v_cmp_eq_u32_e32 vcc, v0, v1
	s_and_saveexec_b64 s[0:1], vcc
	s_cbranch_execz .LBB0_76
	s_add_u32 s10, s26, 0xc0200
	s_addc_u32 s11, s27, 0
	s_mov_b32 s23, 1
	s_mov_b64 s[14:15], 0
	v_mov_b32_e32 v0, 0
	s_branch .LBB0_67

.LBB0_492:
	s_or_b64 exec, exec, s[4:5]
	buffer_inv sc1
	v_cvt_f32_u32_e32 v4, v2
	s_waitcnt vmcnt(1)
	v_readfirstlane_b32 s0, v3
	v_sub_u32_e32 v3, 0, v2
	v_rcp_iflag_f32_e32 v4, v4
	v_add_u32_e32 v5, s0, v1
	v_mul_f32_e32 v4, 0x4f7ffffe, v4
	v_cvt_u32_f32_e32 v4, v4
	v_mul_lo_u32 v1, v3, v4
	v_mul_hi_u32 v1, v4, v1
	v_add_u32_e32 v1, v4, v1
	v_mul_hi_u32 v1, v5, v1
	v_mul_lo_u32 v3, v1, v2
	v_sub_u32_e32 v3, v5, v3
	v_add_u32_e32 v4, 1, v1
	v_cmp_ge_u32_e32 vcc, v3, v2
	s_nop 1
	v_cndmask_b32_e32 v1, v1, v4, vcc
	v_sub_u32_e32 v4, v3, v2
	v_cndmask_b32_e32 v3, v3, v4, vcc
	v_add_u32_e32 v4, 1, v1
	v_cmp_ge_u32_e32 vcc, v3, v2
	v_add_u32_e32 v3, 1, v5
	s_nop 0
	v_cndmask_b32_e32 v1, v1, v4, vcc
	v_mul_lo_u32 v4, v2, v1
	v_add_u32_e32 v2, v4, v2
	v_cmp_ne_u32_e32 vcc, v3, v2
	s_and_saveexec_b64 s[0:1], vcc
	s_xor_b64 s[4:5], exec, s[0:1]
	s_cbranch_execz .LBB0_506
	s_waitcnt lgkmcnt(0)
	v_mov_b32_e32 v0, 0x2000
	global_load_dword v0, v0, s[8:9] offset:1024 sc1
	s_add_u32 s12, s8, 0x2400
	s_addc_u32 s13, s9, 0
	s_waitcnt vmcnt(0)
	v_cmp_eq_u32_e32 vcc, v0, v1
	s_and_saveexec_b64 s[0:1], vcc
	s_cbranch_execz .LBB0_505
	s_add_u32 s10, s26, 0xc0200
	s_addc_u32 s11, s27, 0
	s_mov_b32 s20, 1
	s_mov_b64 s[14:15], 0
	v_mov_b32_e32 v0, 0
	s_branch .LBB0_496

.LBB0_805:
	s_or_b64 exec, exec, s[4:5]
	buffer_inv sc1
	v_cvt_f32_u32_e32 v4, v2
	s_waitcnt vmcnt(1)
	v_readfirstlane_b32 s0, v3
	v_sub_u32_e32 v3, 0, v2
	v_rcp_iflag_f32_e32 v4, v4
	v_add_u32_e32 v5, s0, v1
	v_mul_f32_e32 v4, 0x4f7ffffe, v4
	v_cvt_u32_f32_e32 v4, v4
	v_mul_lo_u32 v1, v3, v4
	v_mul_hi_u32 v1, v4, v1
	v_add_u32_e32 v1, v4, v1
	v_mul_hi_u32 v1, v5, v1
	v_mul_lo_u32 v3, v1, v2
	v_sub_u32_e32 v3, v5, v3
	v_add_u32_e32 v4, 1, v1
	v_cmp_ge_u32_e32 vcc, v3, v2
	s_nop 1
	v_cndmask_b32_e32 v1, v1, v4, vcc
	v_sub_u32_e32 v4, v3, v2
	v_cndmask_b32_e32 v3, v3, v4, vcc
	v_add_u32_e32 v4, 1, v1
	v_cmp_ge_u32_e32 vcc, v3, v2
	v_add_u32_e32 v3, 1, v5
	s_nop 0
	v_cndmask_b32_e32 v1, v1, v4, vcc
	v_mul_lo_u32 v4, v2, v1
	v_add_u32_e32 v2, v4, v2
	v_cmp_ne_u32_e32 vcc, v3, v2
	s_and_saveexec_b64 s[0:1], vcc
	s_xor_b64 s[4:5], exec, s[0:1]
	s_cbranch_execz .LBB0_819
	s_waitcnt lgkmcnt(0)
	v_mov_b32_e32 v0, 0x2000
	global_load_dword v0, v0, s[10:11] offset:1024 sc1
	s_add_u32 s14, s10, 0x2400
	s_addc_u32 s15, s11, 0
	s_waitcnt vmcnt(0)
	v_cmp_eq_u32_e32 vcc, v0, v1
	s_and_saveexec_b64 s[0:1], vcc
	s_cbranch_execz .LBB0_818
	s_add_u32 s12, s26, 0xc0200
	s_addc_u32 s13, s27, 0
	s_mov_b32 s20, 1
	s_mov_b64 s[16:17], 0
	v_mov_b32_e32 v0, 0
	s_branch .LBB0_809

.LBB0_1772:
	s_or_b64 exec, exec, s[6:7]
	buffer_inv sc1
	v_cvt_f32_u32_e32 v4, v2
	s_waitcnt vmcnt(1)
	v_readfirstlane_b32 s0, v3
	v_sub_u32_e32 v3, 0, v2
	v_rcp_iflag_f32_e32 v4, v4
	v_add_u32_e32 v5, s0, v1
	v_mul_f32_e32 v4, 0x4f7ffffe, v4
	v_cvt_u32_f32_e32 v4, v4
	v_mul_lo_u32 v1, v3, v4
	v_mul_hi_u32 v1, v4, v1
	v_add_u32_e32 v1, v4, v1
	v_mul_hi_u32 v1, v5, v1
	v_mul_lo_u32 v3, v1, v2
	v_sub_u32_e32 v3, v5, v3
	v_add_u32_e32 v4, 1, v1
	v_cmp_ge_u32_e32 vcc, v3, v2
	s_nop 1
	v_cndmask_b32_e32 v1, v1, v4, vcc
	v_sub_u32_e32 v4, v3, v2
	v_cndmask_b32_e32 v3, v3, v4, vcc
	v_add_u32_e32 v4, 1, v1
	v_cmp_ge_u32_e32 vcc, v3, v2
	v_add_u32_e32 v3, 1, v5
	s_nop 0
	v_cndmask_b32_e32 v1, v1, v4, vcc
	v_mul_lo_u32 v4, v2, v1
	v_add_u32_e32 v2, v4, v2
	v_cmp_ne_u32_e32 vcc, v3, v2
	s_and_saveexec_b64 s[0:1], vcc
	s_xor_b64 s[0:1], exec, s[0:1]
	s_cbranch_execz .LBB0_1786
	s_waitcnt lgkmcnt(0)
	v_mov_b32_e32 v0, 0x2000
	global_load_dword v0, v0, s[4:5] offset:1024 sc1
	s_add_u32 s10, s4, 0x2400
	s_addc_u32 s11, s5, 0
	s_waitcnt vmcnt(0)
	v_cmp_eq_u32_e32 vcc, v0, v1
	s_and_saveexec_b64 s[6:7], vcc
	s_cbranch_execz .LBB0_1785
	s_add_u32 s8, s26, 0xc0200
	s_addc_u32 s9, s27, 0
	s_mov_b32 s23, 1
	s_mov_b64 s[12:13], 0
	v_mov_b32_e32 v0, 0
	s_branch .LBB0_1776
